# NSA step loop: the 32 packed O-rescale multiplies (v_pk_mul_f32 with broadcast scalar) split into 64 v_mul_f32 (bit-identical)
# baseline (speedup 1.0000x reference)
.LBB0_200:
	s_lshr_b32 s0, s82, 6
	s_lshl_b32 s0, 1, s0
	v_and_b32_e32 v112, s0, v195
	v_cmp_ne_u32_e32 vcc, 0, v112
	s_or_b64 s[14:15], s[10:11], vcc
	s_cmp_lt_i32 s23, 0
	s_cselect_b64 s[4:5], -1, 0
	s_and_b64 s[0:1], s[4:5], exec
	s_cselect_b32 s0, s82, s23
	v_add_u32_e32 v120, s0, v251
	v_ashrrev_i32_e32 v121, 31, v120
	v_lshlrev_b64 v[112:113], 8, v[120:121]
	v_add_u32_e32 v120, 4, v120
	v_ashrrev_i32_e32 v121, 31, v120
	v_lshl_add_u64 v[128:129], s[82:83], 1, v[170:171]
	v_lshlrev_b64 v[120:121], 8, v[120:121]
	v_add_co_u32_e32 v130, vcc, s3, v128
	v_lshl_add_u64 v[116:117], v[158:159], 0, v[112:113]
	v_lshl_add_u64 v[124:125], v[158:159], 0, v[120:121]
	v_addc_co_u32_e32 v131, vcc, 0, v129, vcc
	s_mov_b32 s0, 0x20000
	global_load_dwordx4 v[136:139], v[128:129], off
	s_nop 0
	global_load_dwordx4 v[140:143], v[130:131], off
	s_nop 0
	v_add_co_u32_e32 v130, vcc, s0, v128
	s_mov_b32 s0, 0x30000
	s_nop 0
	v_addc_co_u32_e32 v131, vcc, 0, v129, vcc
	global_load_dwordx4 v[132:135], v[130:131], off
	s_nop 0
	v_add_co_u32_e32 v130, vcc, s0, v128
	v_lshl_add_u32 v166, v144, 1, s82
	s_nop 0
	v_addc_co_u32_e32 v131, vcc, 0, v129, vcc
	global_load_dwordx4 v[128:131], v[130:131], off
	s_nop 0
	s_nop 0
	global_load_dwordx4 v[112:115], v[116:117], off
	s_nop 0
	global_load_dwordx4 v[116:119], v[116:117], off offset:64
	s_nop 0
	global_load_dwordx4 v[120:123], v[124:125], off
	s_nop 0
	global_load_dwordx4 v[124:127], v[124:125], off offset:64
	v_cmp_ge_i32_e32 vcc, v166, v160
	v_cmp_lt_i32_e64 s[0:1], v191, v166
	v_add_u32_e32 v167, 4, v166
	s_and_b64 vcc, s[14:15], vcc
	v_cndmask_b32_e64 v168, 0, v223, s[0:1]
	v_cndmask_b32_e32 v179, v223, v168, vcc
	v_cmp_ge_i32_e32 vcc, v167, v160
	v_cmp_gt_i32_e64 s[0:1], v167, v191
	s_and_b64 vcc, s[14:15], vcc
	v_add_u32_e32 v168, 6, v166
	v_cndmask_b32_e64 v167, 0, v223, s[0:1]
	v_cndmask_b32_e32 v181, v223, v167, vcc
	v_cmp_ge_i32_e32 vcc, v166, v153
	v_cmp_gt_i32_e64 s[0:1], v191, v166
	s_and_b64 s[0:1], s[0:1], vcc
	v_add_u32_e32 v167, 5, v166
	s_and_b64 s[0:1], s[14:15], s[0:1]
	v_cndmask_b32_e64 v183, v223, 0, s[0:1]
	v_cmp_ge_i32_e32 vcc, v167, v160
	v_cmp_gt_i32_e64 s[0:1], v167, v191
	s_and_b64 vcc, s[14:15], vcc
	s_waitcnt vmcnt(8)
	v_mfma_f32_16x16x32_bf16 v[228:231], v[108:111], v[0:3], 0
	v_cndmask_b32_e64 v167, 0, v223, s[0:1]
	v_cndmask_b32_e32 v185, v223, v167, vcc
	v_add_u32_e32 v167, 2, v166
	v_cmp_ge_i32_e32 vcc, v167, v160
	v_cmp_gt_i32_e64 s[0:1], v167, v191
	s_and_b64 vcc, s[14:15], vcc
	v_mfma_f32_16x16x32_bf16 v[232:235], v[100:103], v[0:3], 0
	v_cndmask_b32_e64 v167, 0, v223, s[0:1]
	v_cndmask_b32_e32 v187, v223, v167, vcc
	v_cmp_ge_i32_e32 vcc, v168, v160
	v_cmp_gt_i32_e64 s[0:1], v168, v191
	s_and_b64 vcc, s[14:15], vcc
	v_add_u32_e32 v168, 7, v166
	v_cndmask_b32_e64 v167, 0, v223, s[0:1]
	v_cndmask_b32_e32 v189, v223, v167, vcc
	v_add_u32_e32 v167, 3, v166
	v_sub_u32_e32 v166, v191, v166
	v_cvt_f32_i32_e32 v204, v166
	v_cmp_ge_i32_e32 vcc, v167, v160
	v_cmp_gt_i32_e64 s[0:1], v167, v191
	s_and_b64 vcc, s[14:15], vcc
	v_mfma_f32_16x16x32_bf16 v[228:231], v[104:107], v[4:7], v[228:231]
	v_cndmask_b32_e64 v167, 0, v223, s[0:1]
	v_cndmask_b32_e32 v202, v223, v167, vcc
	v_cmp_ge_i32_e32 vcc, v168, v160
	v_mfma_f32_16x16x32_bf16 v[232:235], v[96:99], v[4:7], v[232:235]
	v_cmp_gt_i32_e64 s[0:1], v168, v191
	s_and_b64 vcc, s[14:15], vcc
	v_mul_f32_e64 v166, -v196, v204
	v_cndmask_b32_e64 v167, 0, v223, s[0:1]
	v_cndmask_b32_e32 v203, v223, v167, vcc
	v_fma_f32 v167, 0, v196, v166
	v_fmamk_f32 v168, v196, 0x40800000, v166
	v_fma_f32 v174, -v196, v204, v196
	v_fmamk_f32 v176, v196, 0x40a00000, v166
	v_fmac_f32_e32 v167, 0x3e38aa3b, v228
	v_fmac_f32_e32 v168, 0x3e38aa3b, v232
	v_fmac_f32_e32 v174, 0x3e38aa3b, v229
	v_fmac_f32_e32 v176, 0x3e38aa3b, v233
	v_add_f32_e32 v167, v179, v167
	v_add_f32_e32 v168, v181, v168
	v_add_f32_e32 v174, v183, v174
	v_add_f32_e32 v182, v185, v176
	v_max_f32_e32 v169, v167, v168
	v_max_f32_e32 v176, v174, v182
	v_max3_f32 v169, v169, s73, v176
	v_fma_f32 v176, 2.0, v196, v166
	v_fmamk_f32 v178, v196, 0x40c00000, v166
	v_fmamk_f32 v180, v196, 0x40400000, v166
	v_fmac_f32_e32 v166, 0x40e00000, v196
	v_fmac_f32_e32 v176, 0x3e38aa3b, v230
	v_fmac_f32_e32 v178, 0x3e38aa3b, v234
	v_fmac_f32_e32 v180, 0x3e38aa3b, v231
	v_fmac_f32_e32 v166, 0x3e38aa3b, v235
	v_add_f32_e32 v176, v187, v176
	v_add_f32_e32 v186, v189, v178
	v_add_f32_e32 v180, v202, v180
	v_add_f32_e32 v166, v203, v166
	v_max_f32_e32 v178, v176, v186
	v_max_f32_e32 v184, v180, v166
	v_max3_f32 v169, v169, v178, v184
	v_mov_b32_e32 v178, v169
	v_mfma_f32_16x16x32_bf16 v[232:235], v[100:103], v[8:11], 0
	v_fma_f32 v205, -v197, v204, v197
	v_permlane16_swap_b32_e32 v178, v169
	v_max_f32_e32 v169, v169, v178
	v_mov_b32_e32 v178, v169
	v_mfma_f32_16x16x32_bf16 v[232:235], v[96:99], v[12:15], v[232:235]
	s_nop 0
	v_permlane32_swap_b32_e32 v178, v169
	v_max3_f32 v201, v172, v169, v178
	v_sub_f32_e32 v167, v167, v201
	v_sub_f32_e32 v169, v172, v201
	v_exp_f32_e32 v172, v167
	v_sub_f32_e32 v167, v174, v201
	v_exp_f32_e32 v174, v167
	v_sub_f32_e32 v167, v176, v201
	v_exp_f32_e32 v176, v167
	v_sub_f32_e32 v167, v180, v201
	v_exp_f32_e32 v178, v167
	v_sub_f32_e32 v167, v168, v201
	v_exp_f32_e32 v180, v167
	v_sub_f32_e32 v167, v182, v201
	v_exp_f32_e32 v184, v167
	v_sub_f32_e32 v167, v186, v201
	v_sub_f32_e32 v166, v166, v201
	v_exp_f32_e32 v186, v167
	v_exp_f32_e32 v188, v166
	v_exp_f32_e32 v182, v169
	v_cvt_pk_bf16_f32 v228, v172, v174
	v_cvt_pk_bf16_f32 v229, v176, v178
	v_cvt_pk_bf16_f32 v230, v180, v184
	v_cvt_pk_bf16_f32 v231, v186, v188
	v_mul_f32_e32 v94, v182, v94
	v_mul_f32_e32 v95, v182, v95
	v_mul_f32_e32 v92, v182, v92
	v_mul_f32_e32 v93, v182, v93
	v_mul_f32_e32 v90, v182, v90
	v_mul_f32_e32 v91, v182, v91
	v_mul_f32_e32 v88, v182, v88
	v_mul_f32_e32 v89, v182, v89
	v_mul_f32_e32 v86, v182, v86
	v_mul_f32_e32 v87, v182, v87
	v_mul_f32_e32 v84, v182, v84
	v_mul_f32_e32 v85, v182, v85
	v_mul_f32_e32 v82, v182, v82
	v_mul_f32_e32 v83, v182, v83
	v_mul_f32_e32 v80, v182, v80
	v_mul_f32_e32 v81, v182, v81
	s_waitcnt vmcnt(4)
	v_mfma_f32_16x16x32_bf16 v[92:95], v[136:139], v[228:231], v[92:95]
	v_mul_f32_e64 v166, -v197, v204
	v_fma_f32 v167, 0, v197, v166
	v_fmamk_f32 v168, v197, 0x40800000, v166
	v_mfma_f32_16x16x32_bf16 v[88:91], v[140:143], v[228:231], v[88:91]
	v_fmac_f32_e32 v168, 0x3e38aa3b, v232
	v_add_f32_e32 v169, v181, v168
	v_mfma_f32_16x16x32_bf16 v[84:87], v[132:135], v[228:231], v[84:87]
	v_mfma_f32_16x16x32_bf16 v[80:83], v[128:131], v[228:231], v[80:83]
	v_mfma_f32_16x16x32_bf16 v[228:231], v[108:111], v[8:11], 0
	v_mfma_f32_16x16x32_bf16 v[228:231], v[104:107], v[12:15], v[228:231]
	s_nop 7
	v_fmac_f32_e32 v205, 0x3e38aa3b, v229
	v_add_f32_e32 v206, v183, v205
	v_fmamk_f32 v205, v197, 0x40a00000, v166
	v_fmac_f32_e32 v167, 0x3e38aa3b, v228
	v_fmac_f32_e32 v205, 0x3e38aa3b, v233
	v_add_f32_e32 v167, v179, v167
	v_add_f32_e32 v207, v185, v205
	v_max_f32_e32 v168, v167, v169
	v_max_f32_e32 v205, v206, v207
	v_max3_f32 v168, v168, s73, v205
	v_fma_f32 v205, 2.0, v197, v166
	v_fmac_f32_e32 v205, 0x3e38aa3b, v230
	v_add_f32_e32 v228, v187, v205
	v_fmamk_f32 v205, v197, 0x40c00000, v166
	v_fmamk_f32 v230, v197, 0x40400000, v166
	v_fmac_f32_e32 v166, 0x40e00000, v197
	v_fmac_f32_e32 v205, 0x3e38aa3b, v234
	v_fmac_f32_e32 v230, 0x3e38aa3b, v231
	v_fmac_f32_e32 v166, 0x3e38aa3b, v235
	v_add_f32_e32 v229, v189, v205
	v_add_f32_e32 v230, v202, v230
	v_add_f32_e32 v231, v203, v166
	v_max_f32_e32 v205, v228, v229
	v_max_f32_e32 v166, v230, v231
	v_max3_f32 v166, v168, v205, v166
	v_mov_b32_e32 v168, v166
	s_nop 1
	v_permlane16_swap_b32_e32 v168, v166
	v_max_f32_e32 v166, v166, v168
	v_mov_b32_e32 v168, v166
	s_nop 1
	v_permlane32_swap_b32_e32 v168, v166
	v_max3_f32 v205, v177, v166, v168
	v_sub_f32_e32 v166, v167, v205
	v_sub_f32_e32 v167, v206, v205
	v_exp_f32_e32 v168, v167
	v_sub_f32_e32 v167, v228, v205
	v_exp_f32_e32 v236, v167
	v_sub_f32_e32 v167, v230, v205
	v_exp_f32_e32 v238, v167
	v_sub_f32_e32 v167, v169, v205
	v_exp_f32_e32 v240, v167
	v_sub_f32_e32 v167, v207, v205
	v_exp_f32_e32 v242, v167
	v_sub_f32_e32 v167, v229, v205
	v_sub_f32_e32 v177, v177, v205
	v_exp_f32_e32 v244, v167
	v_sub_f32_e32 v167, v231, v205
	v_exp_f32_e32 v166, v166
	v_exp_f32_e32 v246, v167
	v_exp_f32_e32 v248, v177
	v_cvt_pk_bf16_f32 v229, v236, v238
	v_cvt_pk_bf16_f32 v228, v166, v168
	v_cvt_pk_bf16_f32 v230, v240, v242
	v_cvt_pk_bf16_f32 v231, v244, v246
	v_mul_f32_e32 v78, v248, v78
	v_mul_f32_e32 v79, v248, v79
	v_mul_f32_e32 v76, v248, v76
	v_mul_f32_e32 v77, v248, v77
	v_mul_f32_e32 v74, v248, v74
	v_mul_f32_e32 v75, v248, v75
	v_mul_f32_e32 v72, v248, v72
	v_mul_f32_e32 v73, v248, v73
	v_mul_f32_e32 v70, v248, v70
	v_mul_f32_e32 v71, v248, v71
	v_mul_f32_e32 v68, v248, v68
	v_mul_f32_e32 v69, v248, v69
	v_mul_f32_e32 v66, v248, v66
	v_mul_f32_e32 v67, v248, v67
	v_mul_f32_e32 v64, v248, v64
	v_mul_f32_e32 v65, v248, v65
	v_mfma_f32_16x16x32_bf16 v[76:79], v[136:139], v[228:231], v[76:79]
	v_mfma_f32_16x16x32_bf16 v[72:75], v[140:143], v[228:231], v[72:75]
	v_mfma_f32_16x16x32_bf16 v[68:71], v[132:135], v[228:231], v[68:71]
	v_mfma_f32_16x16x32_bf16 v[64:67], v[128:131], v[228:231], v[64:67]
	v_mfma_f32_16x16x32_bf16 v[228:231], v[108:111], v[16:19], 0
	v_mul_f32_e64 v167, -v198, v204
	v_fma_f32 v169, 0, v198, v167
	v_fmamk_f32 v177, v198, 0x40800000, v167
	v_mfma_f32_16x16x32_bf16 v[232:235], v[100:103], v[16:19], 0
	v_fma_f32 v207, -v198, v204, v198
	v_mfma_f32_16x16x32_bf16 v[108:111], v[108:111], v[24:27], 0
	v_mfma_f32_16x16x32_bf16 v[100:103], v[100:103], v[24:27], 0
	v_mfma_f32_16x16x32_bf16 v[228:231], v[104:107], v[20:23], v[228:231]
	v_mfma_f32_16x16x32_bf16 v[232:235], v[96:99], v[20:23], v[232:235]
	v_mfma_f32_16x16x32_bf16 v[104:107], v[104:107], v[28:31], v[108:111]
	s_nop 5
	v_fmac_f32_e32 v169, 0x3e38aa3b, v228
	v_fmamk_f32 v228, v198, 0x40a00000, v167
	v_fmac_f32_e32 v177, 0x3e38aa3b, v232
	v_mfma_f32_16x16x32_bf16 v[96:99], v[96:99], v[28:31], v[100:103]
	v_fmac_f32_e32 v207, 0x3e38aa3b, v229
	v_fmac_f32_e32 v228, 0x3e38aa3b, v233
	v_add_f32_e32 v169, v179, v169
	v_mul_f32_e64 v100, -v199, v204
	v_fma_f32 v101, 0, v199, v100
	v_fmac_f32_e32 v101, 0x3e38aa3b, v104
	v_fmamk_f32 v102, v199, 0x40800000, v100
	v_fma_f32 v103, -v199, v204, v199
	v_fmamk_f32 v104, v199, 0x40a00000, v100
	v_add_f32_e32 v177, v181, v177
	v_add_f32_e32 v207, v183, v207
	v_add_f32_e32 v228, v185, v228
	v_fmac_f32_e32 v102, 0x3e38aa3b, v96
	v_fmac_f32_e32 v103, 0x3e38aa3b, v105
	v_fmac_f32_e32 v104, 0x3e38aa3b, v97
	v_max_f32_e32 v206, v169, v177
	v_max_f32_e32 v229, v207, v228
	v_add_f32_e32 v101, v179, v101
	v_add_f32_e32 v96, v181, v102
	v_add_f32_e32 v103, v183, v103
	v_add_f32_e32 v97, v185, v104
	v_max3_f32 v206, v206, s73, v229
	v_fma_f32 v229, 2.0, v198, v167
	v_max_f32_e32 v102, v101, v96
	v_max_f32_e32 v104, v103, v97
	v_fmac_f32_e32 v229, 0x3e38aa3b, v230
	v_fmamk_f32 v230, v198, 0x40c00000, v167
	v_fmamk_f32 v233, v198, 0x40400000, v167
	v_fmac_f32_e32 v167, 0x40e00000, v198
	v_max3_f32 v102, v102, s73, v104
	v_fma_f32 v104, 2.0, v199, v100
	v_fmac_f32_e32 v230, 0x3e38aa3b, v234
	v_fmac_f32_e32 v233, 0x3e38aa3b, v231
	v_fmac_f32_e32 v167, 0x3e38aa3b, v235
	v_fmac_f32_e32 v104, 0x3e38aa3b, v106
	v_fmamk_f32 v105, v199, 0x40c00000, v100
	v_fmamk_f32 v106, v199, 0x40400000, v100
	v_fmac_f32_e32 v100, 0x40e00000, v199
	v_add_f32_e32 v229, v187, v229
	v_add_f32_e32 v230, v189, v230
	v_add_f32_e32 v231, v202, v233
	v_add_f32_e32 v233, v203, v167
	v_fmac_f32_e32 v105, 0x3e38aa3b, v98
	v_fmac_f32_e32 v106, 0x3e38aa3b, v107
	v_fmac_f32_e32 v100, 0x3e38aa3b, v99
	v_max_f32_e32 v232, v229, v230
	v_max_f32_e32 v167, v231, v233
	v_add_f32_e32 v104, v187, v104
	v_add_f32_e32 v98, v189, v105
	v_add_f32_e32 v106, v202, v106
	v_add_f32_e32 v99, v203, v100
	v_max3_f32 v167, v206, v232, v167
	v_max_f32_e32 v105, v104, v98
	v_max_f32_e32 v100, v106, v99
	v_mov_b32_e32 v206, v167
	v_max3_f32 v100, v102, v105, v100
	v_mov_b32_e32 v102, v100
	s_nop 0
	v_permlane16_swap_b32_e32 v206, v167
	s_nop 0
	v_permlane16_swap_b32_e32 v102, v100
	v_max_f32_e32 v167, v167, v206
	v_max_f32_e32 v100, v100, v102
	v_mov_b32_e32 v206, v167
	v_mov_b32_e32 v102, v100
	s_nop 1
	v_permlane32_swap_b32_e32 v206, v167
	v_permlane32_swap_b32_e32 v102, v100
	v_max3_f32 v206, v175, v167, v206
	v_sub_f32_e32 v177, v177, v206
	v_max3_f32 v202, v173, v100, v102
	v_sub_f32_e32 v167, v169, v206
	v_exp_f32_e32 v241, v177
	v_sub_f32_e32 v177, v228, v206
	v_sub_f32_e32 v101, v101, v202
	v_sub_f32_e32 v175, v175, v206
	v_exp_f32_e32 v167, v167
	v_sub_f32_e32 v169, v207, v206
	v_exp_f32_e32 v243, v177
	v_sub_f32_e32 v177, v230, v206
	v_sub_f32_e32 v100, v173, v202
	v_exp_f32_e32 v173, v101
	v_sub_f32_e32 v101, v103, v202
	v_sub_f32_e32 v96, v96, v202
	v_exp_f32_e32 v169, v169
	v_sub_f32_e32 v207, v229, v206
	v_exp_f32_e32 v245, v177
	v_sub_f32_e32 v177, v233, v206
	v_exp_f32_e32 v249, v175
	v_exp_f32_e32 v175, v101
	v_sub_f32_e32 v101, v104, v202
	v_exp_f32_e32 v181, v96
	v_sub_f32_e32 v96, v97, v202
	v_exp_f32_e32 v237, v207
	v_sub_f32_e32 v207, v231, v206
	v_exp_f32_e32 v247, v177
	v_exp_f32_e32 v177, v101
	v_sub_f32_e32 v101, v106, v202
	v_exp_f32_e32 v185, v96
	v_sub_f32_e32 v96, v98, v202
	v_exp_f32_e32 v239, v207
	v_exp_f32_e32 v179, v101
	v_exp_f32_e32 v187, v96
	v_sub_f32_e32 v96, v99, v202
	v_pk_add_f32 v[228:229], v[166:167], 0 op_sel_hi:[1,0]
	v_exp_f32_e32 v189, v96
	v_pk_add_f32 v[96:97], v[172:173], 0 op_sel_hi:[1,0]
	v_pk_add_f32 v[228:229], v[168:169], v[228:229]
	v_pk_add_f32 v[96:97], v[174:175], v[96:97]
	v_pk_add_f32 v[228:229], v[236:237], v[228:229]
	v_pk_add_f32 v[96:97], v[176:177], v[96:97]
	v_pk_add_f32 v[228:229], v[238:239], v[228:229]
	v_exp_f32_e32 v183, v100
	v_pk_add_f32 v[96:97], v[178:179], v[96:97]
	v_pk_add_f32 v[228:229], v[240:241], v[228:229]
	v_pk_add_f32 v[96:97], v[180:181], v[96:97]
	v_pk_add_f32 v[228:229], v[242:243], v[228:229]
	v_pk_add_f32 v[96:97], v[184:185], v[96:97]
	v_pk_add_f32 v[228:229], v[244:245], v[228:229]
	v_pk_add_f32 v[96:97], v[186:187], v[96:97]
	v_pk_add_f32 v[228:229], v[246:247], v[228:229]
	v_mov_b32_e32 v166, v249
	v_pk_add_f32 v[96:97], v[188:189], v[96:97]
	v_mov_b32_e32 v100, v183
	v_pk_fma_f32 v[156:157], v[156:157], v[248:249], v[228:229]
	v_cvt_pk_bf16_f32 v228, v167, v169
	v_cvt_pk_bf16_f32 v229, v237, v239
	v_cvt_pk_bf16_f32 v230, v241, v243
	v_cvt_pk_bf16_f32 v231, v245, v247
	v_mul_f32_e32 v62, v166, v62
	v_mul_f32_e32 v63, v166, v63
	v_mul_f32_e32 v60, v166, v60
	v_mul_f32_e32 v61, v166, v61
	v_mul_f32_e32 v58, v166, v58
	v_mul_f32_e32 v59, v166, v59
	v_mul_f32_e32 v56, v166, v56
	v_mul_f32_e32 v57, v166, v57
	v_mul_f32_e32 v54, v166, v54
	v_mul_f32_e32 v55, v166, v55
	v_mul_f32_e32 v52, v166, v52
	v_mul_f32_e32 v53, v166, v53
	v_mul_f32_e32 v50, v166, v50
	v_mul_f32_e32 v51, v166, v51
	v_mul_f32_e32 v48, v166, v48
	v_mul_f32_e32 v49, v166, v49
	v_pk_fma_f32 v[154:155], v[154:155], v[182:183], v[96:97]
	v_cvt_pk_bf16_f32 v96, v173, v175
	v_cvt_pk_bf16_f32 v97, v177, v179
	v_cvt_pk_bf16_f32 v98, v181, v185
	v_cvt_pk_bf16_f32 v99, v187, v189
	v_mul_f32_e32 v46, v100, v46
	v_mul_f32_e32 v47, v100, v47
	v_mul_f32_e32 v44, v100, v44
	v_mul_f32_e32 v45, v100, v45
	v_mul_f32_e32 v42, v100, v42
	v_mul_f32_e32 v43, v100, v43
	v_mul_f32_e32 v40, v100, v40
	v_mul_f32_e32 v41, v100, v41
	v_mul_f32_e32 v38, v100, v38
	v_mul_f32_e32 v39, v100, v39
	v_mul_f32_e32 v36, v100, v36
	v_mul_f32_e32 v37, v100, v37
	v_mul_f32_e32 v34, v100, v34
	v_mul_f32_e32 v35, v100, v35
	v_mul_f32_e32 v32, v100, v32
	v_mul_f32_e32 v33, v100, v33
	v_mfma_f32_16x16x32_bf16 v[60:63], v[136:139], v[228:231], v[60:63]
	v_mfma_f32_16x16x32_bf16 v[56:59], v[140:143], v[228:231], v[56:59]
	v_mfma_f32_16x16x32_bf16 v[52:55], v[132:135], v[228:231], v[52:55]
	v_mfma_f32_16x16x32_bf16 v[48:51], v[128:131], v[228:231], v[48:51]
	v_mfma_f32_16x16x32_bf16 v[44:47], v[136:139], v[96:99], v[44:47]
	v_mfma_f32_16x16x32_bf16 v[40:43], v[140:143], v[96:99], v[40:43]
	v_mfma_f32_16x16x32_bf16 v[36:39], v[132:135], v[96:99], v[36:39]
	v_mfma_f32_16x16x32_bf16 v[32:35], v[128:131], v[96:99], v[32:35]
	s_waitcnt vmcnt(0)
	s_and_b64 vcc, exec, s[4:5]
	s_cbranch_vccnz .LBB0_203
	v_mov_b64_e32 v[108:109], v[112:113]
	v_mov_b64_e32 v[104:105], v[116:117]
	v_mov_b64_e32 v[100:101], v[120:121]
	v_mov_b64_e32 v[96:97], v[124:125]
	s_mov_b32 s82, s23
	s_mov_b32 s4, s24
	v_mov_b64_e32 v[110:111], v[114:115]
	v_mov_b64_e32 v[106:107], v[118:119]
	v_mov_b64_e32 v[102:103], v[122:123]
	v_mov_b64_e32 v[98:99], v[126:127]
	v_mov_b32_e32 v172, v201
	v_mov_b32_e32 v177, v205
	v_mov_b32_e32 v175, v206
	v_mov_b32_e32 v173, v202
	s_andn2_b64 vcc, exec, s[12:13]
	s_mov_b64 s[0:1], -1
	s_cbranch_vccz .LBB0_193
	s_branch .LBB0_198
